# NA attention: relative-position bias loads batched (16 ds_read2 then one wait) instead of 32 serialised exec-masked LDS round trips
# speedup vs baseline: 1.0147x; 1.0147x over previous
.LBB0_515:
	s_xor_b64 s[82:83], s[88:89], -1
	s_and_b32 s94, s33, 1
	s_cmp_lt_i32 s33, s40
	s_cselect_b64 s[76:77], -1, 0
	s_cmp_ge_i32 s33, s40
	s_cselect_b64 s[90:91], -1, 0
	s_add_i32 s0, s41, s33
	v_cmp_ge_i32_e32 vcc, s0, v206
	v_cmp_lt_i32_e64 s[0:1], s0, v207
	s_and_b64 s[0:1], vcc, s[0:1]
	s_or_b64 s[90:91], s[90:91], s[0:1]
	s_and_saveexec_b64 s[0:1], s[90:91]
	s_cbranch_execz .LBB0_588
	s_mul_i32 s33, s94, 0x3400
	v_add_u32_e32 v52, s33, v209
	ds_read_b128 v[48:51], v52
	ds_read_b128 v[80:83], v52 offset:32
	ds_read_b128 v[84:87], v52 offset:6656
	ds_read_b128 v[88:91], v52 offset:6688
	ds_read_b128 v[92:95], v52 offset:64
	ds_read_b128 v[96:99], v52 offset:96
	ds_read_b128 v[100:103], v52 offset:6720
	ds_read_b128 v[104:107], v52 offset:6752
	s_waitcnt lgkmcnt(0)
	v_mfma_f32_32x32x16_bf16 v[64:79], v[48:51], v[114:117], v[32:47]
	v_mov_b64_e32 v[62:63], v[46:47]
	v_mov_b64_e32 v[60:61], v[44:45]
	v_mov_b64_e32 v[58:59], v[42:43]
	v_mov_b64_e32 v[56:57], v[40:41]
	v_mov_b64_e32 v[54:55], v[38:39]
	v_mov_b64_e32 v[52:53], v[36:37]
	v_mov_b64_e32 v[50:51], v[34:35]
	v_mov_b64_e32 v[48:49], v[32:33]
	v_mfma_f32_32x32x16_bf16 v[64:79], v[80:83], v[118:121], v[64:79]
	s_mul_i32 s33, s94, 0x2400
	v_add_u32_e32 v80, s33, v210
	ds_read_b128 v[166:169], v80 offset:26624
	ds_read_b128 v[158:161], v80 offset:26656
	ds_read_b128 v[162:165], v80 offset:31232
	ds_read_b128 v[154:157], v80 offset:31264
	ds_read_b128 v[150:153], v80 offset:26688
	ds_read_b128 v[146:149], v80 offset:31296
	ds_read_b128 v[142:145], v80 offset:26720
	ds_read_b128 v[138:141], v80 offset:31328
	v_mfma_f32_32x32x16_bf16 v[48:63], v[84:87], v[114:117], v[48:63]
	v_mfma_f32_32x32x16_bf16 v[48:63], v[88:91], v[118:121], v[48:63]
	v_mfma_f32_32x32x16_bf16 v[64:79], v[92:95], v[122:125], v[64:79]
	v_mfma_f32_32x32x16_bf16 v[48:63], v[100:103], v[122:125], v[48:63]
	v_mfma_f32_32x32x16_bf16 v[64:79], v[96:99], v[126:129], v[64:79]
	v_mfma_f32_32x32x16_bf16 v[48:63], v[104:107], v[126:129], v[48:63]
	s_andn2_b64 vcc, exec, s[76:77]
	s_cbranch_vccnz .LBB0_582
	ds_read2_b32 v[80:81], v211 offset1:32
	ds_read2_b32 v[82:83], v211 offset0:1 offset1:33
	ds_read2_b32 v[84:85], v211 offset0:2 offset1:34
	ds_read2_b32 v[86:87], v211 offset0:3 offset1:35
	ds_read2_b32 v[88:89], v211 offset0:8 offset1:40
	ds_read2_b32 v[90:91], v211 offset0:9 offset1:41
	ds_read2_b32 v[92:93], v211 offset0:10 offset1:42
	ds_read2_b32 v[94:95], v211 offset0:11 offset1:43
	ds_read2_b32 v[96:97], v211 offset0:16 offset1:48
	ds_read2_b32 v[98:99], v211 offset0:17 offset1:49
	ds_read2_b32 v[100:101], v211 offset0:18 offset1:50
	ds_read2_b32 v[102:103], v211 offset0:19 offset1:51
	ds_read2_b32 v[104:105], v211 offset0:24 offset1:56
	ds_read2_b32 v[106:107], v211 offset0:25 offset1:57
	ds_read2_b32 v[108:109], v211 offset0:26 offset1:58
	ds_read2_b32 v[110:111], v211 offset0:27 offset1:59
	s_waitcnt lgkmcnt(0)
	v_add_f32_e32 v64, v64, v80
	v_mov_b32_e32 v80, 0xff800000
	v_cndmask_b32_e64 v64, v80, v64, s[10:11]
	v_add_f32_e32 v48, v48, v81
	v_cndmask_b32_e64 v48, v80, v48, s[12:13]
	v_add_f32_e32 v65, v65, v82
	v_cndmask_b32_e64 v65, v80, v65, s[14:15]
	v_add_f32_e32 v49, v49, v83
	v_cndmask_b32_e64 v49, v80, v49, s[16:17]
	v_add_f32_e32 v66, v66, v84
	v_cndmask_b32_e64 v66, v80, v66, s[18:19]
	v_add_f32_e32 v50, v50, v85
	v_cndmask_b32_e64 v50, v80, v50, s[20:21]
	v_add_f32_e32 v67, v67, v86
	v_cndmask_b32_e64 v67, v80, v67, s[22:23]
	v_add_f32_e32 v51, v51, v87
	v_cndmask_b32_e64 v51, v80, v51, s[24:25]
	v_add_f32_e32 v68, v68, v88
	v_cndmask_b32_e64 v68, v80, v68, s[26:27]
	v_add_f32_e32 v52, v52, v89
	v_cndmask_b32_e64 v52, v80, v52, s[28:29]
	v_add_f32_e32 v69, v69, v90
	v_cndmask_b32_e64 v69, v80, v69, s[30:31]
	v_add_f32_e32 v53, v53, v91
	v_cndmask_b32_e64 v53, v80, v53, s[34:35]
	v_add_f32_e32 v70, v70, v92
	v_cndmask_b32_e64 v70, v80, v70, s[36:37]
	v_add_f32_e32 v54, v54, v93
	v_cndmask_b32_e64 v54, v80, v54, s[8:9]
	v_add_f32_e32 v71, v71, v94
	v_cndmask_b32_e64 v71, v80, v71, s[4:5]
	v_add_f32_e32 v55, v55, v95
	v_cndmask_b32_e64 v55, v80, v55, s[42:43]
	v_add_f32_e32 v72, v72, v96
	v_cndmask_b32_e64 v72, v80, v72, s[44:45]
	v_add_f32_e32 v56, v56, v97
	v_cndmask_b32_e64 v56, v80, v56, s[46:47]
	v_add_f32_e32 v73, v73, v98
	v_cndmask_b32_e64 v73, v80, v73, s[48:49]
	v_add_f32_e32 v57, v57, v99
	v_cndmask_b32_e64 v57, v80, v57, s[50:51]
	v_add_f32_e32 v74, v74, v100
	v_cndmask_b32_e64 v74, v80, v74, s[52:53]
	v_add_f32_e32 v58, v58, v101
	v_cndmask_b32_e64 v58, v80, v58, s[54:55]
	v_add_f32_e32 v75, v75, v102
	v_cndmask_b32_e64 v75, v80, v75, s[56:57]
	v_add_f32_e32 v59, v59, v103
	v_cndmask_b32_e64 v59, v80, v59, s[58:59]
	v_add_f32_e32 v76, v76, v104
	v_cndmask_b32_e64 v76, v80, v76, s[60:61]
	v_add_f32_e32 v60, v60, v105
	v_cndmask_b32_e64 v60, v80, v60, s[62:63]
	v_add_f32_e32 v77, v77, v106
	v_cndmask_b32_e64 v77, v80, v77, s[64:65]
	v_add_f32_e32 v61, v61, v107
	v_cndmask_b32_e64 v61, v80, v61, s[66:67]
	v_add_f32_e32 v78, v78, v108
	v_cndmask_b32_e64 v78, v80, v78, s[68:69]
	v_add_f32_e32 v62, v62, v109
	v_cndmask_b32_e64 v62, v80, v62, s[70:71]
	v_add_f32_e32 v79, v79, v110
	v_cndmask_b32_e64 v79, v80, v79, s[72:73]
	v_add_f32_e32 v63, v63, v111
	v_cndmask_b32_e64 v63, v80, v63, s[74:75]
